# RWKV token-local stores (M1) transposed through the per-wave LDS slot, as the G1 epilogue
# speedup vs baseline: 1.0113x; 1.0003x over previous
.LBB0_342:
	v_or_b32_e32 v176, s0, v221
	s_waitcnt lgkmcnt(0)
	v_mbcnt_lo_u32_b32 v232, -1, 0
	v_mbcnt_hi_u32_b32 v232, -1, v232
	v_and_b32_e32 v233, 15, v232
	v_lshrrev_b32_e32 v234, 4, v232
	v_lshrrev_b32_e32 v198, 2, v233
	v_xor_b32_e32 v198, v198, v234
	v_lshlrev_b32_e32 v198, 4, v198
	v_lshl_or_b32 v198, v233, 6, v198
	s_lshl_b32 s100, s89, 11
	s_add_i32 s100, s100, 0x20000
	v_add_u32_e32 v198, s100, v198
	v_lshl_add_u32 v199, v232, 4, s100
	v_lshrrev_b32_e32 v202, 2, v232
	v_sub_u32_e32 v202, v202, v233
	v_mul_i32_i24_e32 v202, 0xc00, v202
	v_and_b32_e32 v203, 3, v232
	v_xor_b32_e32 v203, v203, v234
	v_sub_u32_e32 v203, v203, v234
	v_lshlrev_b32_e32 v203, 4, v203
	v_add_u32_e32 v202, v202, v203
	v_ashrrev_i32_e32 v203, 31, v202
	v_lshrrev_b32_e32 v204, 2, v232
	v_sub_u32_e32 v204, v204, v233
	v_mul_i32_i24_e32 v204, 0x200, v204
	v_and_b32_e32 v205, 3, v232
	v_xor_b32_e32 v205, v205, v234
	v_sub_u32_e32 v205, v205, v234
	v_lshlrev_b32_e32 v205, 4, v205
	v_add_u32_e32 v204, v204, v205
	v_ashrrev_i32_e32 v205, 31, v204
	v_mov_b64_e32 v[0:1], s[10:11]
	v_mad_i64_i32 v[0:1], s[4:5], v176, s86, v[0:1]
	s_mov_b64 s[4:5], 0x2040c00
	s_nop 0
	v_lshl_add_u64 v[180:181], v[0:1], 0, s[4:5]
	v_bitop3_b32 v0, s0, v241, v221 bitop3:0xc8
	v_cmp_eq_u32_e32 vcc, 0, v0
	v_mov_b32_e32 v0, 0xffffec00
	v_mov_b32_e32 v159, v195
	v_cndmask_b32_e64 v185, -1, 0, vcc
	v_cndmask_b32_e64 v184, v0, 0, vcc
	v_lshl_add_u64 v[0:1], v[180:181], 0, v[194:195]
	global_load_dwordx4 v[116:119], v[0:1], off
	v_lshl_add_u64 v[182:183], v[180:181], 0, v[184:185]
	v_lshl_add_u64 v[0:1], v[182:183], 0, v[194:195]
	global_load_dwordx4 v[186:189], v[0:1], off
	global_load_dwordx4 v[80:83], v[122:123], off offset:3072
	global_load_dwordx4 v[206:209], v[122:123], off offset:3088
	v_lshl_add_u64 v[0:1], v[180:181], 0, v[158:159]
	global_load_dwordx4 v[104:107], v[0:1], off
	v_lshl_add_u64 v[0:1], v[182:183], 0, v[158:159]
	v_mov_b32_e32 v161, v195
	global_load_dwordx4 v[84:87], v[0:1], off
	global_load_dwordx4 v[108:111], v[122:123], off offset:3216
	global_load_dwordx4 v[112:115], v[122:123], off offset:3200
	v_lshl_add_u64 v[0:1], v[180:181], 0, v[160:161]
	global_load_dwordx4 v[88:91], v[0:1], off
	v_lshl_add_u64 v[0:1], v[182:183], 0, v[160:161]
	v_mov_b32_e32 v163, v195
	global_load_dwordx4 v[92:95], v[0:1], off
	global_load_dwordx4 v[96:99], v[122:123], off offset:3328
	global_load_dwordx4 v[100:103], v[122:123], off offset:3344
	v_lshl_add_u64 v[0:1], v[180:181], 0, v[162:163]
	v_cndmask_b32_e64 v178, 1.0, 0, vcc
	global_load_dwordx4 v[64:67], v[0:1], off
	v_lshl_add_u64 v[0:1], v[182:183], 0, v[162:163]
	global_load_dwordx4 v[68:71], v[0:1], off
	global_load_dwordx4 v[72:75], v[122:123], off offset:3456
	global_load_dwordx4 v[76:79], v[122:123], off offset:3472
	global_load_dwordx4 v[60:63], v[124:125], off
	global_load_dwordx4 v[56:59], v[124:125], off offset:64
	global_load_dwordx4 v[52:55], v[124:125], off offset:128
	global_load_dwordx4 v[48:51], v[124:125], off offset:192
	global_load_dwordx4 v[44:47], v[124:125], off offset:1024
	global_load_dwordx4 v[40:43], v[124:125], off offset:1088
	global_load_dwordx4 v[28:31], v[124:125], off offset:1152
	global_load_dwordx4 v[24:27], v[124:125], off offset:1216
	global_load_dwordx4 v[20:23], v[126:127], off
	global_load_dwordx4 v[0:3], v[128:129], off
	global_load_dwordx4 v[4:7], v[130:131], off
	global_load_dwordx4 v[8:11], v[132:133], off
	global_load_dwordx4 v[12:15], v[134:135], off
	global_load_dwordx4 v[16:19], v[136:137], off
	global_load_dwordx4 v[32:35], v[138:139], off
	global_load_dwordx4 v[36:39], v[140:141], off
	v_ashrrev_i32_e32 v177, 31, v176
	v_lshlrev_b64 v[212:213], 9, v[176:177]
	v_lshl_add_u64 v[212:213], v[156:157], 0, v[212:213]
	s_waitcnt vmcnt(0) lgkmcnt(0)
	v_and_b32_e32 v163, 0xffff0000, v116
	v_lshlrev_b32_e32 v165, 16, v117
	v_and_b32_e32 v167, 0xffff0000, v117
	v_lshlrev_b32_e32 v161, 16, v118
	v_and_b32_e32 v159, 0xffff0000, v118
	v_lshlrev_b32_e32 v118, 16, v119
	v_and_b32_e32 v117, 0xffff0000, v119
	v_and_b32_e32 v119, 0xffff0000, v186
	v_lshlrev_b32_e32 v169, 16, v187
	v_fma_f32 v119, v178, v119, -v163
	v_and_b32_e32 v171, 0xffff0000, v187
	v_fmac_f32_e32 v163, v81, v119
	v_fma_f32 v81, v178, v169, -v165
	v_lshlrev_b32_e32 v173, 16, v188
	v_fmac_f32_e32 v165, v82, v81
	v_fma_f32 v81, v178, v171, -v167
	v_and_b32_e32 v175, 0xffff0000, v188
	v_fmac_f32_e32 v167, v83, v81
	v_fma_f32 v81, v178, v173, -v161
	v_lshlrev_b32_e32 v187, 16, v189
	v_fmac_f32_e32 v161, v206, v81
	v_fma_f32 v81, v178, v175, -v159
	v_and_b32_e32 v188, 0xffff0000, v189
	v_fmac_f32_e32 v159, v207, v81
	v_fma_f32 v81, v178, v187, -v118
	v_fmac_f32_e32 v118, v208, v81
	v_fma_f32 v81, v178, v188, -v117
	v_fmac_f32_e32 v117, v209, v81
	v_lshlrev_b32_e32 v81, 16, v186
	v_lshlrev_b32_e32 v82, 16, v116
	v_fma_f32 v81, v178, v81, -v82
	v_fmac_f32_e32 v82, v80, v81
	v_add_f32_e32 v80, v82, v82
	v_add_f32_e32 v81, v163, v163
	v_mul_f32_e32 v80, 0x3fb8aa3b, v80
	v_mul_f32_e32 v81, 0x3fb8aa3b, v81
	v_exp_f32_e32 v80, v80
	v_exp_f32_e32 v81, v81
	v_add_f32_e32 v117, v117, v117
	v_mul_f32_e32 v117, 0x3fb8aa3b, v117
	v_exp_f32_e32 v117, v117
	v_pk_add_f32 v[80:81], v[80:81], 1.0 op_sel_hi:[1,0]
	v_mov_b32_e32 v169, v195
	v_mov_b32_e32 v171, v195
	v_mov_b32_e32 v173, v195
	v_mov_b32_e32 v175, v195
	v_rcp_f32_e32 v81, v81
	s_nop 0
	v_mul_f32_e32 v81, 2.0, v81
	v_rcp_f32_e32 v80, v80
	s_nop 0
	v_mul_f32_e32 v80, 2.0, v80
	v_add_f32_e32 v82, v165, v165
	v_add_f32_e32 v83, v167, v167
	v_mul_f32_e32 v82, 0x3fb8aa3b, v82
	v_mul_f32_e32 v83, 0x3fb8aa3b, v83
	v_exp_f32_e32 v82, v82
	v_exp_f32_e32 v83, v83
	v_pk_add_f32 v[80:81], v[80:81], 1.0 op_sel_hi:[1,0] neg_lo:[1,0] neg_hi:[1,0]
	v_pk_add_f32 v[82:83], v[82:83], 1.0 op_sel_hi:[1,0]
	s_nop 0
	v_cvt_pk_bf16_f32 v80, v80, v81
	v_rcp_f32_e32 v83, v83
	s_nop 0
	v_mul_f32_e32 v83, 2.0, v83
	v_rcp_f32_e32 v82, v82
	s_nop 0
	v_mul_f32_e32 v82, 2.0, v82
	v_add_f32_e32 v116, v161, v161
	v_mul_f32_e32 v116, 0x3fb8aa3b, v116
	v_exp_f32_e32 v186, v116
	v_add_f32_e32 v116, v159, v159
	v_mul_f32_e32 v116, 0x3fb8aa3b, v116
	v_exp_f32_e32 v187, v116
	v_pk_add_f32 v[82:83], v[82:83], 1.0 op_sel_hi:[1,0] neg_lo:[1,0] neg_hi:[1,0]
	v_mov_b32_e32 v165, v195
	v_cvt_pk_bf16_f32 v81, v82, v83
	v_pk_add_f32 v[186:187], v[186:187], 1.0 op_sel_hi:[1,0]
	v_mov_b32_e32 v167, v195
	v_rcp_f32_e32 v187, v187
	s_nop 0
	v_mul_f32_e32 v187, 2.0, v187
	v_rcp_f32_e32 v186, v186
	s_nop 0
	v_mul_f32_e32 v186, 2.0, v186
	v_add_f32_e32 v116, v118, v118
	v_mul_f32_e32 v116, 0x3fb8aa3b, v116
	v_exp_f32_e32 v116, v116
	v_pk_add_f32 v[186:187], v[186:187], 1.0 op_sel_hi:[1,0] neg_lo:[1,0] neg_hi:[1,0]
	v_pk_add_f32 v[116:117], v[116:117], 1.0 op_sel_hi:[1,0]
	s_nop 0
	v_cvt_pk_bf16_f32 v82, v186, v187
	v_rcp_f32_e32 v117, v117
	s_nop 0
	v_mul_f32_e32 v117, 2.0, v117
	v_rcp_f32_e32 v116, v116
	s_nop 0
	v_mul_f32_e32 v116, 2.0, v116
	v_pk_add_f32 v[116:117], v[116:117], 1.0 op_sel_hi:[1,0] neg_lo:[1,0] neg_hi:[1,0]
	v_lshlrev_b32_e32 v118, 16, v84
	v_cvt_pk_bf16_f32 v83, v116, v117
	v_lshlrev_b32_e32 v116, 16, v104
	v_and_b32_e32 v117, 0xffff0000, v104
	v_and_b32_e32 v119, 0xffff0000, v84
	v_lshlrev_b32_e32 v104, 16, v105
	v_and_b32_e32 v105, 0xffff0000, v105
	v_lshlrev_b32_e32 v84, 16, v85
	v_and_b32_e32 v85, 0xffff0000, v85
	v_pk_fma_f32 v[84:85], v[178:179], v[84:85], v[104:105] op_sel_hi:[0,1,1] neg_lo:[0,0,1] neg_hi:[0,0,1]
	v_pk_fma_f32 v[104:105], v[114:115], v[84:85], v[104:105]
	v_lshlrev_b32_e32 v84, 16, v106
	v_and_b32_e32 v85, 0xffff0000, v106
	v_lshlrev_b32_e32 v114, 16, v86
	v_and_b32_e32 v115, 0xffff0000, v86
	v_pk_fma_f32 v[114:115], v[178:179], v[114:115], v[84:85] op_sel_hi:[0,1,1] neg_lo:[0,0,1] neg_hi:[0,0,1]
	v_pk_fma_f32 v[108:109], v[108:109], v[114:115], v[84:85]
	v_lshlrev_b32_e32 v84, 16, v107
	v_and_b32_e32 v85, 0xffff0000, v107
	v_lshlrev_b32_e32 v86, 16, v87
	v_and_b32_e32 v87, 0xffff0000, v87
	v_pk_fma_f32 v[86:87], v[178:179], v[86:87], v[84:85] op_sel_hi:[0,1,1] neg_lo:[0,0,1] neg_hi:[0,0,1]
	v_pk_fma_f32 v[106:107], v[110:111], v[86:87], v[84:85]
	v_cvt_pk_bf16_f32 v85, v104, v105
	v_cvt_pk_bf16_f32 v87, v106, v107
	v_and_b32_e32 v104, 0xffff0000, v88
	v_lshlrev_b32_e32 v105, 16, v89
	v_and_b32_e32 v106, 0xffff0000, v89
	v_and_b32_e32 v89, 0xffff0000, v92
	v_cvt_pk_bf16_f32 v86, v108, v109
	v_lshlrev_b32_e32 v109, 16, v93
	v_fma_f32 v89, v178, v89, -v104
	v_and_b32_e32 v93, 0xffff0000, v93
	v_fmac_f32_e32 v104, v97, v89
	v_fma_f32 v89, v178, v109, -v105
	v_lshlrev_b32_e32 v107, 16, v90
	v_lshlrev_b32_e32 v110, 16, v94
	v_fmac_f32_e32 v105, v98, v89
	v_fma_f32 v89, v178, v93, -v106
	v_and_b32_e32 v90, 0xffff0000, v90
	v_and_b32_e32 v94, 0xffff0000, v94
	v_fmac_f32_e32 v106, v99, v89
	v_fma_f32 v89, v178, v110, -v107
	v_lshlrev_b32_e32 v108, 16, v91
	v_lshlrev_b32_e32 v111, 16, v95
	v_fmac_f32_e32 v107, v100, v89
	v_fma_f32 v89, v178, v94, -v90
	v_and_b32_e32 v91, 0xffff0000, v91
	v_and_b32_e32 v95, 0xffff0000, v95
	v_fmac_f32_e32 v90, v101, v89
	v_fma_f32 v89, v178, v111, -v108
	v_fmac_f32_e32 v108, v102, v89
	v_fma_f32 v89, v178, v95, -v91
	v_fmac_f32_e32 v91, v103, v89
	v_lshlrev_b32_e32 v89, 16, v92
	v_lshlrev_b32_e32 v88, 16, v88
	v_fma_f32 v89, v178, v89, -v88
	v_fmac_f32_e32 v88, v96, v89
	v_mul_f32_e32 v88, 0xbfb8aa3b, v88
	v_mul_f32_e32 v89, 0xbfb8aa3b, v104
	v_exp_f32_e32 v88, v88
	v_exp_f32_e32 v89, v89
	v_pk_fma_f32 v[118:119], v[178:179], v[118:119], v[116:117] op_sel_hi:[0,1,1] neg_lo:[0,0,1] neg_hi:[0,0,1]
	v_pk_fma_f32 v[112:113], v[112:113], v[118:119], v[116:117]
	v_pk_add_f32 v[88:89], v[88:89], 1.0 op_sel_hi:[1,0]
	s_nop 0
	v_cvt_pk_bf16_f32 v84, v112, v113
	v_rcp_f32_e32 v92, v89
	s_nop 0
	v_mfma_f32_16x16x32_bf16 v[16:19], v[16:19], v[84:87], 0
	v_rcp_f32_e32 v93, v88
	v_mul_f32_e32 v88, 0xbfb8aa3b, v105
	v_mul_f32_e32 v89, 0xbfb8aa3b, v106
	v_exp_f32_e32 v88, v88
	v_exp_f32_e32 v89, v89
	s_nop 0
	v_pk_add_f32 v[88:89], v[88:89], 1.0 op_sel_hi:[1,0]
	s_nop 0
	v_rcp_f32_e32 v94, v89
	v_rcp_f32_e32 v95, v88
	v_mul_f32_e32 v88, 0xbfb8aa3b, v107
	v_mul_f32_e32 v89, 0xbfb8aa3b, v90
	v_exp_f32_e32 v88, v88
	v_exp_f32_e32 v89, v89
	s_nop 0
	v_pk_add_f32 v[88:89], v[88:89], 1.0 op_sel_hi:[1,0]
	s_nop 0
	v_rcp_f32_e32 v90, v89
	v_rcp_f32_e32 v96, v88
	v_mul_f32_e32 v88, 0xbfb8aa3b, v108
	v_mul_f32_e32 v89, 0xbfb8aa3b, v91
	v_exp_f32_e32 v88, v88
	v_exp_f32_e32 v89, v89
	v_cvt_pk_bf16_f32 v90, v96, v90
	v_lshlrev_b32_e32 v96, 16, v67
	v_and_b32_e32 v67, 0xffff0000, v67
	v_pk_add_f32 v[88:89], v[88:89], 1.0 op_sel_hi:[1,0]
	s_nop 0
	v_rcp_f32_e32 v91, v89
	v_rcp_f32_e32 v97, v88
	v_cvt_pk_bf16_f32 v88, v93, v92
	v_cvt_pk_bf16_f32 v89, v95, v94
	v_and_b32_e32 v92, 0xffff0000, v64
	v_lshlrev_b32_e32 v93, 16, v65
	v_and_b32_e32 v94, 0xffff0000, v65
	v_and_b32_e32 v65, 0xffff0000, v68
	v_cvt_pk_bf16_f32 v91, v97, v91
	v_lshlrev_b32_e32 v97, 16, v69
	v_fma_f32 v65, v178, v65, -v92
	v_and_b32_e32 v69, 0xffff0000, v69
	v_fmac_f32_e32 v92, v73, v65
	v_fma_f32 v65, v178, v97, -v93
	v_lshlrev_b32_e32 v95, 16, v66
	v_lshlrev_b32_e32 v98, 16, v70
	v_fmac_f32_e32 v93, v74, v65
	v_fma_f32 v65, v178, v69, -v94
	v_and_b32_e32 v66, 0xffff0000, v66
	v_and_b32_e32 v70, 0xffff0000, v70
	v_fmac_f32_e32 v94, v75, v65
	v_fma_f32 v65, v178, v98, -v95
	v_lshlrev_b32_e32 v99, 16, v71
	v_fmac_f32_e32 v95, v76, v65
	v_fma_f32 v65, v178, v70, -v66
	v_and_b32_e32 v71, 0xffff0000, v71
	v_fmac_f32_e32 v66, v77, v65
	v_fma_f32 v65, v178, v99, -v96
	v_fmac_f32_e32 v96, v78, v65
	v_fma_f32 v65, v178, v71, -v67
	v_fmac_f32_e32 v67, v79, v65
	v_lshlrev_b32_e32 v65, 16, v68
	v_lshlrev_b32_e32 v64, 16, v64
	v_fma_f32 v65, v178, v65, -v64
	v_fmac_f32_e32 v64, v72, v65
	v_mul_f32_e32 v64, 0xbfb8aa3b, v64
	v_mul_f32_e32 v65, 0xbfb8aa3b, v92
	v_exp_f32_e32 v64, v64
	v_exp_f32_e32 v65, v65
	v_mfma_f32_16x16x32_bf16 v[28:31], v[28:31], v[88:91], 0
	v_add_f32_e64 v64, v64, 1.0
	v_add_f32_e64 v65, v65, 1.0
	v_mfma_f32_16x16x32_bf16 v[52:55], v[52:55], v[88:91], 0
	v_rcp_f32_e32 v68, v65
	v_rcp_f32_e32 v69, v64
	v_mul_f32_e32 v64, 0xbfb8aa3b, v93
	v_mul_f32_e32 v65, 0xbfb8aa3b, v94
	v_exp_f32_e32 v64, v64
	v_exp_f32_e32 v65, v65
	s_nop 0
	v_pk_add_f32 v[64:65], v[64:65], 1.0 op_sel_hi:[1,0]
	s_nop 0
	v_rcp_f32_e32 v70, v65
	v_rcp_f32_e32 v71, v64
	v_mul_f32_e32 v64, 0xbfb8aa3b, v95
	v_mul_f32_e32 v65, 0xbfb8aa3b, v66
	v_exp_f32_e32 v64, v64
	v_exp_f32_e32 v65, v65
	v_mfma_f32_16x16x32_bf16 v[92:95], v[56:59], v[84:87], 0
	v_add_f32_e64 v64, v64, 1.0
	v_add_f32_e64 v65, v65, 1.0
	v_mfma_f32_16x16x32_bf16 v[56:59], v[40:43], v[84:87], 0
	v_rcp_f32_e32 v66, v65
	v_rcp_f32_e32 v72, v64
	v_mul_f32_e32 v64, 0xbfb8aa3b, v96
	v_mul_f32_e32 v65, 0xbfb8aa3b, v67
	v_exp_f32_e32 v64, v64
	v_exp_f32_e32 v65, v65
	v_cvt_pk_bf16_f32 v66, v72, v66
	v_mfma_f32_16x16x32_bf16 v[96:99], v[60:63], v[80:83], 0
	v_add_f32_e64 v64, v64, 1.0
	v_add_f32_e64 v65, v65, 1.0
	v_mfma_f32_16x16x32_bf16 v[60:63], v[44:47], v[80:83], 0
	v_rcp_f32_e32 v67, v65
	v_rcp_f32_e32 v73, v64
	v_cvt_pk_bf16_f32 v64, v69, v68
	v_cvt_pk_bf16_f32 v65, v71, v70
	v_cvt_pk_bf16_f32 v67, v73, v67
	s_nop 1
	v_mfma_f32_16x16x32_bf16 v[40:43], v[24:27], v[64:67], v[28:31]
	v_mfma_f32_16x16x32_bf16 v[24:27], v[0:3], v[84:87], 0
	v_mfma_f32_16x16x32_bf16 v[0:3], v[4:7], v[88:91], 0
	v_mfma_f32_16x16x32_bf16 v[0:3], v[8:11], v[64:67], v[0:3]
	v_lshl_add_u64 v[8:9], v[180:181], 0, v[164:165]
	global_load_dwordx4 v[186:189], v[8:9], off
	v_lshl_add_u64 v[8:9], v[8:9], 0, v[184:185]
	v_mfma_f32_16x16x32_bf16 v[4:7], v[32:35], v[88:91], 0
	global_load_dwordx4 v[216:219], v[8:9], off
	global_load_dwordx4 v[222:225], v[142:143], off offset:16
	global_load_dwordx4 v[208:211], v[142:143], off
	v_lshl_add_u64 v[8:9], v[180:181], 0, v[166:167]
	global_load_dwordx4 v[72:75], v[8:9], off
	v_lshl_add_u64 v[8:9], v[182:183], 0, v[166:167]
	v_mfma_f32_16x16x32_bf16 v[48:51], v[48:51], v[64:67], v[52:55]
	v_cvt_pk_bf16_f32 v0, v0, v1
	v_cvt_pk_bf16_f32 v1, v2, v3
	s_waitcnt vmcnt(0) lgkmcnt(0)
	v_lshlrev_b32_e32 v184, 16, v186
	v_mfma_f32_16x16x32_bf16 v[4:7], v[36:39], v[64:67], v[4:7]
	global_load_dwordx4 v[68:71], v[8:9], off
	global_load_dwordx4 v[64:67], v[142:143], off offset:1040
	global_load_dwordx4 v[100:103], v[142:143], off offset:1024
	v_lshl_add_u64 v[8:9], v[180:181], 0, v[168:169]
	global_load_dwordx4 v[44:47], v[8:9], off
	v_lshl_add_u64 v[8:9], v[182:183], 0, v[168:169]
	v_mfma_f32_16x16x32_bf16 v[28:31], v[20:23], v[80:83], 0
	v_and_b32_e32 v185, 0xffff0000, v186
	v_lshlrev_b32_e32 v190, 16, v216
	v_and_b32_e32 v191, 0xffff0000, v216
	v_mfma_f32_16x16x32_bf16 v[20:23], v[12:15], v[80:83], 0
	global_load_dwordx4 v[36:39], v[8:9], off
	global_load_dwordx4 v[32:35], v[142:143], off offset:2064
	global_load_dwordx4 v[52:55], v[142:143], off offset:2048
	global_load_dwordx4 v[84:87], v[144:145], off offset:16
	global_load_dwordx4 v[116:119], v[144:145], off
	global_load_dwordx4 v[88:91], v[146:147], off offset:16
	global_load_dwordx4 v[112:115], v[146:147], off
	global_load_dwordx4 v[8:11], v[148:149], off
	global_load_dwordx4 v[12:15], v[148:149], off offset:16
	global_load_dwordx4 v[80:83], v[150:151], off offset:16
	global_load_dwordx4 v[108:111], v[150:151], off
	global_load_dwordx4 v[76:79], v[152:153], off offset:16
	global_load_dwordx4 v[104:107], v[152:153], off
	v_pk_fma_f32 v[190:191], v[178:179], v[190:191], v[184:185] op_sel_hi:[0,1,1] neg_lo:[0,0,1] neg_hi:[0,0,1]
	v_pk_fma_f32 v[208:209], v[208:209], v[190:191], v[184:185]
	v_lshlrev_b32_e32 v184, 16, v187
	v_and_b32_e32 v185, 0xffff0000, v187
	v_lshlrev_b32_e32 v186, 16, v217
	v_and_b32_e32 v187, 0xffff0000, v217
	v_pk_fma_f32 v[186:187], v[178:179], v[186:187], v[184:185] op_sel_hi:[0,1,1] neg_lo:[0,0,1] neg_hi:[0,0,1]
	v_pk_fma_f32 v[214:215], v[210:211], v[186:187], v[184:185]
	v_lshlrev_b32_e32 v184, 16, v188
	v_and_b32_e32 v185, 0xffff0000, v188
	v_lshlrev_b32_e32 v186, 16, v218
	v_and_b32_e32 v187, 0xffff0000, v218
	v_pk_fma_f32 v[186:187], v[178:179], v[186:187], v[184:185] op_sel_hi:[0,1,1] neg_lo:[0,0,1] neg_hi:[0,0,1]
	v_pk_fma_f32 v[216:217], v[222:223], v[186:187], v[184:185]
	v_lshlrev_b32_e32 v184, 16, v189
	v_and_b32_e32 v185, 0xffff0000, v189
	v_lshlrev_b32_e32 v186, 16, v219
	v_and_b32_e32 v187, 0xffff0000, v219
	v_pk_fma_f32 v[186:187], v[178:179], v[186:187], v[184:185] op_sel_hi:[0,1,1] neg_lo:[0,0,1] neg_hi:[0,0,1]
	v_pk_fma_f32 v[218:219], v[224:225], v[186:187], v[184:185]
	v_cvt_pk_bf16_f32 v2, v4, v5
	v_cvt_pk_bf16_f32 v3, v6, v7
	s_waitcnt vmcnt(0)
	v_add_f32_e32 v60, v60, v84
	v_add_f32_e32 v96, v96, v116
	v_max_f32_e64 v116, -v96, 0
	v_mul_f32_e64 v96, |v96|, s26
	v_exp_f32_e32 v96, v96
	v_add_f32_e32 v97, v97, v117
	v_add_f32_e32 v92, v92, v112
	v_max_f32_e64 v112, -v97, 0
	v_add_f32_e32 v96, 1.0, v96
	v_cmp_gt_f32_e32 vcc, s6, v96
	v_mul_f32_e64 v97, |v97|, s26
	v_exp_f32_e32 v97, v97
	v_cndmask_b32_e64 v159, 0, 32, vcc
	v_ldexp_f32 v96, v96, v159
	v_log_f32_e32 v96, v96
	v_add_f32_e32 v97, 1.0, v97
	v_add_f32_e32 v93, v93, v113
	v_mul_f32_e32 v92, 0xbfb8aa3b, v92
	v_mul_f32_e32 v159, 0x3f317217, v96
	v_fma_f32 v159, v96, s34, -v159
	v_fmac_f32_e32 v159, 0x3377d1cf, v96
	v_fmac_f32_e32 v159, 0x3f317217, v96
	v_cmp_lt_f32_e64 s[0:1], |v96|, s35
	v_mul_f32_e32 v93, 0xbfb8aa3b, v93
	v_exp_f32_e32 v92, v92
	v_cndmask_b32_e64 v96, v96, v159, s[0:1]
	v_cndmask_b32_e32 v159, 0, v242, vcc
	v_sub_f32_e32 v96, v96, v159
	v_cmp_gt_f32_e32 vcc, s6, v97
	v_add_f32_e32 v96, v116, v96
	v_exp_f32_e32 v93, v93
	v_cndmask_b32_e64 v116, 0, 32, vcc
	v_ldexp_f32 v97, v97, v116
	v_log_f32_e32 v97, v97
	v_pk_add_f32 v[92:93], v[92:93], 1.0 op_sel_hi:[1,0]
	s_waitcnt lgkmcnt(0)
	v_and_b32_e32 v117, 0xffff0000, v68
	v_and_b32_e32 v113, 0xffff0000, v72
	v_mul_f32_e32 v116, 0x3f317217, v97
	v_fma_f32 v116, v97, s34, -v116
	v_fmac_f32_e32 v116, 0x3377d1cf, v97
	v_fmac_f32_e32 v116, 0x3f317217, v97
	v_cmp_lt_f32_e64 s[0:1], |v97|, s35
	v_add_f32_e32 v61, v61, v85
	v_add_f32_e32 v56, v56, v88
	v_cndmask_b32_e64 v97, v97, v116, s[0:1]
	v_cndmask_b32_e32 v116, 0, v242, vcc
	v_sub_f32_e32 v97, v97, v116
	v_lshlrev_b32_e32 v116, 16, v68
	v_add_f32_e32 v97, v112, v97
	v_lshlrev_b32_e32 v112, 16, v72
	v_pk_fma_f32 v[116:117], v[178:179], v[116:117], v[112:113] op_sel_hi:[0,1,1] neg_lo:[0,0,1] neg_hi:[0,0,1]
	v_pk_fma_f32 v[184:185], v[100:101], v[116:117], v[112:113]
	v_add_f32_e32 v57, v57, v89
	v_rcp_f32_e32 v117, v93
	v_mul_f32_e32 v56, 0xbfb8aa3b, v56
	v_mul_f32_e32 v57, 0xbfb8aa3b, v57
	v_exp_f32_e32 v56, v56
	v_rcp_f32_e32 v116, v92
	v_add_f32_e32 v68, v98, v118
	v_max_f32_e64 v72, -v68, 0
	v_mul_f32_e64 v68, |v68|, s26
	v_exp_f32_e32 v68, v68
	v_pk_add_f32 v[92:93], v[116:117], -1.0 op_sel_hi:[1,0]
	v_exp_f32_e32 v57, v57
	v_pk_fma_f32 v[92:93], v[108:109], v[92:93], 1.0 op_sel_hi:[1,1,0]
	v_add_f32_e32 v68, 1.0, v68
	v_cmp_gt_f32_e32 vcc, s6, v68
	v_pk_mul_f32 v[92:93], v[184:185], v[92:93]
	v_and_b32_e32 v85, 0xffff0000, v74
	v_cndmask_b32_e64 v98, 0, 32, vcc
	v_ldexp_f32 v68, v68, v98
	v_log_f32_e32 v68, v68
	v_pk_mul_f32 v[100:101], v[208:209], v[92:93]
	v_lshlrev_b32_e32 v88, 16, v70
	v_fma_f32 v159, v104, v100, 0
	v_mul_f32_e32 v98, 0x3f317217, v68
	v_fma_f32 v98, v68, s34, -v98
	v_fmac_f32_e32 v98, 0x3377d1cf, v68
	v_fmac_f32_e32 v98, 0x3f317217, v68
	v_cmp_lt_f32_e64 s[0:1], |v68|, s35
	v_fmac_f32_e32 v159, v105, v101
	v_lshlrev_b32_e32 v100, 16, v73
	v_cndmask_b32_e64 v68, v68, v98, s[0:1]
	v_cndmask_b32_e32 v98, 0, v242, vcc
	v_sub_f32_e32 v68, v68, v98
	v_add_f32_e32 v68, v72, v68
	v_sub_f32_e32 v68, -0.5, v68
	v_mul_f32_e32 v68, 0x3fb8aa3b, v68
	v_exp_f32_e32 v68, v68
	v_and_b32_e32 v101, 0xffff0000, v73
	v_and_b32_e32 v89, 0xffff0000, v70
	v_pk_add_f32 v[56:57], v[56:57], 1.0 op_sel_hi:[1,0]
	v_xor_b32_e32 v72, 0x80000000, v68
	v_add_f32_e32 v68, v94, v114
	v_mul_f32_e32 v68, 0xbfb8aa3b, v68
	v_exp_f32_e32 v98, v68
	v_add_f32_e32 v68, v99, v119
	v_max_f32_e64 v94, -v68, 0
	v_mul_f32_e64 v68, |v68|, s26
	v_exp_f32_e32 v68, v68
	v_add_f32_e32 v62, v62, v86
	v_add_f32_e32 v58, v58, v90
	v_add_f32_e32 v59, v59, v91
	v_add_f32_e32 v68, 1.0, v68
	v_cmp_gt_f32_e32 vcc, s6, v68
	v_mul_f32_e32 v58, 0xbfb8aa3b, v58
	v_mul_f32_e32 v59, 0xbfb8aa3b, v59
	v_cndmask_b32_e64 v99, 0, 32, vcc
	v_ldexp_f32 v68, v68, v99
	v_log_f32_e32 v68, v68
	v_exp_f32_e32 v58, v58
	v_exp_f32_e32 v59, v59
	v_sub_f32_e32 v96, -0.5, v96
	v_mul_f32_e32 v99, 0x3f317217, v68
	v_fma_f32 v99, v68, s34, -v99
	v_fmac_f32_e32 v99, 0x3377d1cf, v68
	v_fmac_f32_e32 v99, 0x3f317217, v68
	v_cmp_lt_f32_e64 s[0:1], |v68|, s35
	v_pk_add_f32 v[58:59], v[58:59], 1.0 op_sel_hi:[1,0]
	v_sub_f32_e32 v97, -0.5, v97
	v_cndmask_b32_e64 v68, v68, v99, s[0:1]
	v_cndmask_b32_e32 v99, 0, v242, vcc
	v_sub_f32_e32 v68, v68, v99
	v_add_f32_e32 v68, v94, v68
	v_sub_f32_e32 v68, -0.5, v68
	v_mul_f32_e32 v68, 0x3fb8aa3b, v68
	v_exp_f32_e32 v68, v68
	v_mul_f32_e32 v96, 0x3fb8aa3b, v96
	v_mul_f32_e32 v97, 0x3fb8aa3b, v97
	v_exp_f32_e32 v96, v96
	v_xor_b32_e32 v94, 0x80000000, v68
	v_add_f32_e32 v68, v95, v115
	v_mul_f32_e32 v68, 0xbfb8aa3b, v68
	v_exp_f32_e32 v99, v68
	v_lshlrev_b32_e32 v68, 16, v69
	v_and_b32_e32 v69, 0xffff0000, v69
	v_pk_fma_f32 v[68:69], v[178:179], v[68:69], v[100:101] op_sel_hi:[0,1,1] neg_lo:[0,0,1] neg_hi:[0,0,1]
	v_pk_fma_f32 v[186:187], v[102:103], v[68:69], v[100:101]
	v_pk_add_f32 v[68:69], v[98:99], 1.0 op_sel_hi:[1,0]
	v_exp_f32_e32 v97, v97
	v_xor_b32_e32 v96, 0x80000000, v96
	v_xor_b32_e32 v97, 0x80000000, v97
	v_pk_mul_f32 v[8:9], v[184:185], v[8:9]
	v_rcp_f32_e32 v119, v69
	v_pk_mul_f32 v[10:11], v[186:187], v[10:11]
	v_max_f32_e64 v73, -v60, 0
	v_mul_f32_e64 v60, |v60|, s26
	v_exp_f32_e32 v60, v60
	v_rcp_f32_e32 v118, v68
	s_nop 0
	v_pk_add_f32 v[68:69], v[118:119], -1.0 op_sel_hi:[1,0]
	v_add_f32_e32 v60, 1.0, v60
	v_cmp_gt_f32_e32 vcc, s6, v60
	v_pk_fma_f32 v[68:69], v[110:111], v[68:69], 1.0 op_sel_hi:[1,1,0]
	s_nop 0
	v_cndmask_b32_e64 v84, 0, 32, vcc
	v_ldexp_f32 v60, v60, v84
	v_log_f32_e32 v60, v60
	v_pk_mul_f32 v[68:69], v[186:187], v[68:69]
	v_mul_f32_e32 v84, 0x3f317217, v60
	v_fma_f32 v84, v60, s34, -v84
	v_fmac_f32_e32 v84, 0x3377d1cf, v60
	v_fmac_f32_e32 v84, 0x3f317217, v60
	v_cmp_lt_f32_e64 s[0:1], |v60|, s35
	v_pk_mul_f32 v[98:99], v[214:215], v[68:69]
	s_nop 0
	v_cndmask_b32_e64 v60, v60, v84, s[0:1]
	v_cndmask_b32_e32 v84, 0, v242, vcc
	v_sub_f32_e32 v60, v60, v84
	v_add_f32_e32 v60, v73, v60
	v_max_f32_e64 v73, -v61, 0
	v_mul_f32_e64 v61, |v61|, s26
	v_exp_f32_e32 v61, v61
	v_fmac_f32_e32 v159, v106, v98
	v_fmac_f32_e32 v159, v107, v99
	v_sub_f32_e32 v60, -0.5, v60
	v_add_f32_e32 v61, 1.0, v61
	v_cmp_gt_f32_e32 vcc, s6, v61
	v_mul_f32_e32 v60, 0x3fb8aa3b, v60
	v_exp_f32_e32 v60, v60
	v_cndmask_b32_e64 v84, 0, 32, vcc
	v_ldexp_f32 v61, v61, v84
	v_log_f32_e32 v61, v61
	v_xor_b32_e32 v60, 0x80000000, v60
	v_mul_f32_e32 v84, 0x3f317217, v61
	v_fma_f32 v84, v61, s34, -v84
	v_fmac_f32_e32 v84, 0x3377d1cf, v61
	v_fmac_f32_e32 v84, 0x3f317217, v61
	v_cmp_lt_f32_e64 s[0:1], |v61|, s35
	s_nop 1
	v_cndmask_b32_e64 v61, v61, v84, s[0:1]
	v_cndmask_b32_e32 v84, 0, v242, vcc
	v_sub_f32_e32 v61, v61, v84
	v_lshlrev_b32_e32 v84, 16, v74
	v_pk_fma_f32 v[88:89], v[178:179], v[88:89], v[84:85] op_sel_hi:[0,1,1] neg_lo:[0,0,1] neg_hi:[0,0,1]
	v_pk_fma_f32 v[190:191], v[64:65], v[88:89], v[84:85]
	v_add_f32_e32 v61, v73, v61
	v_sub_f32_e32 v61, -0.5, v61
	v_mul_f32_e32 v61, 0x3fb8aa3b, v61
	v_rcp_f32_e32 v189, v57
	v_exp_f32_e32 v61, v61
	v_pk_mul_f32 v[6:7], v[190:191], v[12:13]
	v_rcp_f32_e32 v188, v56
	s_nop 0
	v_pk_add_f32 v[56:57], v[188:189], -1.0 op_sel_hi:[1,0]
	v_xor_b32_e32 v61, 0x80000000, v61
	v_pk_fma_f32 v[56:57], v[80:81], v[56:57], 1.0 op_sel_hi:[1,1,0]
	v_pk_mul_f32 v[12:13], v[6:7], v[6:7]
	v_pk_mul_f32 v[56:57], v[190:191], v[56:57]
	s_nop 0
	v_pk_mul_f32 v[64:65], v[216:217], v[56:57]
	s_nop 0
	v_fmac_f32_e32 v159, v76, v64
	v_max_f32_e64 v64, -v62, 0
	v_mul_f32_e64 v62, |v62|, s26
	v_exp_f32_e32 v62, v62
	v_fmac_f32_e32 v159, v77, v65
	v_add_f32_e32 v62, 1.0, v62
	v_cmp_gt_f32_e32 vcc, s6, v62
	s_nop 1
	v_cndmask_b32_e64 v65, 0, 32, vcc
	v_ldexp_f32 v62, v62, v65
	v_log_f32_e32 v62, v62
	s_nop 0
	v_mul_f32_e32 v65, 0x3f317217, v62
	v_fma_f32 v65, v62, s34, -v65
	v_fmac_f32_e32 v65, 0x3377d1cf, v62
	v_fmac_f32_e32 v65, 0x3f317217, v62
	v_cmp_lt_f32_e64 s[0:1], |v62|, s35
	s_nop 1
	v_cndmask_b32_e64 v62, v62, v65, s[0:1]
	v_cndmask_b32_e32 v65, 0, v242, vcc
	v_sub_f32_e32 v62, v62, v65
	v_add_f32_e32 v62, v64, v62
	v_sub_f32_e32 v62, -0.5, v62
	v_mul_f32_e32 v62, 0x3fb8aa3b, v62
	v_exp_f32_e32 v62, v62
	v_and_b32_e32 v65, 0xffff0000, v71
	v_xor_b32_e32 v70, 0x80000000, v62
	v_add_f32_e32 v62, v63, v87
	v_max_f32_e64 v63, -v62, 0
	v_mul_f32_e64 v62, |v62|, s26
	v_exp_f32_e32 v62, v62
	s_nop 0
	v_add_f32_e32 v62, 1.0, v62
	v_cmp_gt_f32_e32 vcc, s6, v62
	s_nop 1
	v_cndmask_b32_e64 v64, 0, 32, vcc
	v_ldexp_f32 v62, v62, v64
	v_log_f32_e32 v62, v62
	s_nop 0
	v_mul_f32_e32 v64, 0x3f317217, v62
	v_fma_f32 v64, v62, s34, -v64
	v_fmac_f32_e32 v64, 0x3377d1cf, v62
	v_fmac_f32_e32 v64, 0x3f317217, v62
	v_cmp_lt_f32_e64 s[0:1], |v62|, s35
	s_nop 1
	v_cndmask_b32_e64 v62, v62, v64, s[0:1]
	v_cndmask_b32_e32 v64, 0, v242, vcc
	v_sub_f32_e32 v62, v62, v64
	v_add_f32_e32 v62, v63, v62
	v_sub_f32_e32 v62, -0.5, v62
	v_mul_f32_e32 v62, 0x3fb8aa3b, v62
	v_exp_f32_e32 v62, v62
	v_and_b32_e32 v63, 0xffff0000, v75
	v_lshlrev_b32_e32 v64, 16, v71
	v_xor_b32_e32 v73, 0x80000000, v62
	v_lshlrev_b32_e32 v62, 16, v75
	v_pk_fma_f32 v[64:65], v[178:179], v[64:65], v[62:63] op_sel_hi:[0,1,1] neg_lo:[0,0,1] neg_hi:[0,0,1]
	v_pk_fma_f32 v[210:211], v[66:67], v[64:65], v[62:63]
	v_rcp_f32_e32 v207, v59
	v_rcp_f32_e32 v206, v58
	s_nop 0
	v_pk_add_f32 v[58:59], v[206:207], -1.0 op_sel_hi:[1,0]
	v_lshlrev_b32_e32 v64, 16, v36
	v_pk_fma_f32 v[58:59], v[82:83], v[58:59], 1.0 op_sel_hi:[1,1,0]
	v_and_b32_e32 v65, 0xffff0000, v36
	v_pk_mul_f32 v[58:59], v[210:211], v[58:59]
	v_lshlrev_b32_e32 v36, 16, v37
	v_pk_mul_f32 v[62:63], v[218:219], v[58:59]
	v_and_b32_e32 v37, 0xffff0000, v37
	v_fmac_f32_e32 v159, v78, v62
	v_fmac_f32_e32 v159, v79, v63
	v_lshlrev_b32_e32 v62, 16, v44
	v_and_b32_e32 v63, 0xffff0000, v44
	v_lshlrev_b32_e32 v44, 16, v45
	v_and_b32_e32 v45, 0xffff0000, v45
	v_pk_fma_f32 v[36:37], v[178:179], v[36:37], v[44:45] op_sel_hi:[0,1,1] neg_lo:[0,0,1] neg_hi:[0,0,1]
	v_pk_fma_f32 v[36:37], v[54:55], v[36:37], v[44:45]
	v_lshlrev_b32_e32 v44, 16, v46
	v_and_b32_e32 v45, 0xffff0000, v46
	v_lshlrev_b32_e32 v54, 16, v38
	v_and_b32_e32 v55, 0xffff0000, v38
	v_pk_fma_f32 v[54:55], v[178:179], v[54:55], v[44:45] op_sel_hi:[0,1,1] neg_lo:[0,0,1] neg_hi:[0,0,1]
	v_pk_fma_f32 v[44:45], v[32:33], v[54:55], v[44:45]
	v_lshlrev_b32_e32 v32, 16, v47
	v_and_b32_e32 v33, 0xffff0000, v47
	v_lshlrev_b32_e32 v38, 16, v39
	v_and_b32_e32 v39, 0xffff0000, v39
	v_pk_fma_f32 v[38:39], v[178:179], v[38:39], v[32:33] op_sel_hi:[0,1,1] neg_lo:[0,0,1] neg_hi:[0,0,1]
	v_pk_fma_f32 v[64:65], v[178:179], v[64:65], v[62:63] op_sel_hi:[0,1,1] neg_lo:[0,0,1] neg_hi:[0,0,1]
	v_pk_fma_f32 v[38:39], v[34:35], v[38:39], v[32:33]
	v_cvt_pk_bf16_f32 v32, v208, v209
	v_cvt_pk_bf16_f32 v33, v214, v215
	v_cvt_pk_bf16_f32 v34, v216, v217
	v_cvt_pk_bf16_f32 v35, v218, v219
	v_mad_i64_i32 v[208:209], s[0:1], v176, s23, v[154:155]
	v_pk_fma_f32 v[52:53], v[52:53], v[64:65], v[62:63]
	ds_write_b128 v198, v[32:35]
	ds_read_b128 v[232:235], v199
	v_lshl_add_u64 v[230:231], v[208:209], 0, v[202:203]
	s_nop 1
	v_cvt_pk_bf16_f32 v32, v92, v93
	v_cvt_pk_bf16_f32 v33, v68, v69
	v_cvt_pk_bf16_f32 v34, v56, v57
	v_cvt_pk_bf16_f32 v35, v58, v59
	ds_write_b128 v198, v[32:35] offset:1024
	ds_read_b128 v[246:249], v199 offset:1024
	v_lshl_add_u64 v[250:251], v[208:209], 0, v[202:203]
	s_waitcnt lgkmcnt(2)
	global_store_dwordx4 v[230:231], v[232:235], off
	s_nop 1
	v_cvt_pk_bf16_f32 v32, v52, v53
	v_cvt_pk_bf16_f32 v33, v36, v37
	v_cvt_pk_bf16_f32 v34, v44, v45
	v_cvt_pk_bf16_f32 v35, v38, v39
	ds_write_b128 v198, v[32:35]
	ds_read_b128 v[232:235], v199
	v_lshl_add_u64 v[230:231], v[208:209], 0, v[202:203]
	s_waitcnt lgkmcnt(2)
	global_store_dwordx4 v[250:251], v[246:249], off offset:512
	s_nop 1
	v_cvt_pk_bf16_f32 v32, v96, v97
	v_cvt_pk_bf16_f32 v33, v72, v94
	v_cvt_pk_bf16_f32 v34, v60, v61
	v_cvt_pk_bf16_f32 v35, v70, v73
	ds_write_b128 v198, v[32:35] offset:1024
	ds_read_b128 v[246:249], v199 offset:1024
	v_lshl_add_u64 v[250:251], v[208:209], 0, v[202:203]
	s_waitcnt lgkmcnt(2)
	global_store_dwordx4 v[230:231], v[232:235], off offset:1024
	s_nop 1
	v_cvt_pk_bf16_f32 v32, v48, v49
	v_cvt_pk_bf16_f32 v33, v50, v51
	v_cvt_pk_bf16_f32 v34, v40, v41
	v_cvt_pk_bf16_f32 v35, v42, v43
	ds_write_b128 v198, v[32:35]
	ds_read_b128 v[232:235], v199
	v_lshl_add_u64 v[230:231], v[212:213], 0, v[204:205]
	s_waitcnt lgkmcnt(2)
	global_store_dwordx4 v[250:251], v[246:249], off offset:2560
	s_nop 1
	v_lshl_add_u64 v[32:33], v[180:181], 0, v[170:171]
	global_load_dwordx4 v[108:111], v[32:33], off
	v_lshl_add_u64 v[32:33], v[182:183], 0, v[170:171]
	global_load_dwordx4 v[112:115], v[32:33], off
	global_load_dwordx4 v[104:107], v[142:143], off offset:144
	global_load_dwordx4 v[214:217], v[142:143], off offset:128
	v_lshl_add_u64 v[32:33], v[180:181], 0, v[172:173]
	global_load_dwordx4 v[60:63], v[32:33], off
	v_lshl_add_u64 v[32:33], v[182:183], 0, v[172:173]
	global_load_dwordx4 v[56:59], v[32:33], off
	global_load_dwordx4 v[52:55], v[142:143], off offset:1168
	global_load_dwordx4 v[84:87], v[142:143], off offset:1152
	v_lshl_add_u64 v[32:33], v[180:181], 0, v[174:175]
	global_load_dwordx4 v[40:43], v[32:33], off
	v_lshl_add_u64 v[32:33], v[182:183], 0, v[174:175]
	global_load_dwordx4 v[36:39], v[32:33], off
	s_nop 0
	global_load_dwordx4 v[32:35], v[142:143], off offset:2192
	global_load_dwordx4 v[44:47], v[142:143], off offset:2176
	global_load_dwordx4 v[64:67], v[144:145], off offset:144
	global_load_dwordx4 v[96:99], v[144:145], off offset:128
	global_load_dwordx4 v[80:83], v[146:147], off offset:144
	global_load_dwordx4 v[100:103], v[146:147], off offset:128
	global_load_dwordx4 v[68:71], v[148:149], off offset:144
	global_load_dwordx4 v[48:51], v[148:149], off offset:128
	global_load_dwordx4 v[76:79], v[150:151], off offset:144
	global_load_dwordx4 v[92:95], v[150:151], off offset:128
	global_load_dwordx4 v[72:75], v[152:153], off offset:144
	global_load_dwordx4 v[88:91], v[152:153], off offset:128
	s_waitcnt vmcnt(0) lgkmcnt(0)
	v_lshlrev_b32_e32 v180, 16, v108
	v_and_b32_e32 v181, 0xffff0000, v108
	v_add_f32_e32 v28, v28, v96
	v_max_f32_e64 v96, -v28, 0
	v_mul_f32_e64 v28, |v28|, s26
	v_lshlrev_b32_e32 v182, 16, v112
	v_and_b32_e32 v183, 0xffff0000, v112
	v_lshlrev_b32_e32 v108, 16, v109
	v_and_b32_e32 v109, 0xffff0000, v109
	v_lshlrev_b32_e32 v112, 16, v113
	v_and_b32_e32 v113, 0xffff0000, v113
	v_exp_f32_e32 v28, v28
	v_pk_fma_f32 v[182:183], v[178:179], v[182:183], v[180:181] op_sel_hi:[0,1,1] neg_lo:[0,0,1] neg_hi:[0,0,1]
	v_pk_fma_f32 v[112:113], v[178:179], v[112:113], v[108:109] op_sel_hi:[0,1,1] neg_lo:[0,0,1] neg_hi:[0,0,1]
	v_pk_fma_f32 v[180:181], v[214:215], v[182:183], v[180:181]
	v_pk_fma_f32 v[108:109], v[216:217], v[112:113], v[108:109]
	v_lshlrev_b32_e32 v112, 16, v110
	v_and_b32_e32 v113, 0xffff0000, v110
	v_lshlrev_b32_e32 v182, 16, v114
	v_and_b32_e32 v183, 0xffff0000, v114
	v_pk_fma_f32 v[182:183], v[178:179], v[182:183], v[112:113] op_sel_hi:[0,1,1] neg_lo:[0,0,1] neg_hi:[0,0,1]
	v_pk_fma_f32 v[104:105], v[104:105], v[182:183], v[112:113]
	v_lshlrev_b32_e32 v110, 16, v111
	v_and_b32_e32 v111, 0xffff0000, v111
	v_lshlrev_b32_e32 v112, 16, v115
	v_and_b32_e32 v113, 0xffff0000, v115
	v_add_f32_e32 v28, 1.0, v28
	v_pk_fma_f32 v[112:113], v[178:179], v[112:113], v[110:111] op_sel_hi:[0,1,1] neg_lo:[0,0,1] neg_hi:[0,0,1]
	v_cmp_gt_f32_e32 vcc, s6, v28
	v_pk_fma_f32 v[106:107], v[106:107], v[112:113], v[110:111]
	v_add_f32_e32 v24, v24, v100
	v_cndmask_b32_e64 v110, 0, 32, vcc
	v_ldexp_f32 v28, v28, v110
	v_log_f32_e32 v28, v28
	v_add_f32_e32 v25, v25, v101
	v_mul_f32_e32 v24, 0xbfb8aa3b, v24
	v_mul_f32_e32 v25, 0xbfb8aa3b, v25
	v_mul_f32_e32 v110, 0x3f317217, v28
	v_fma_f32 v110, v28, s34, -v110
	v_fmac_f32_e32 v110, 0x3377d1cf, v28
	v_fmac_f32_e32 v110, 0x3f317217, v28
	v_cmp_lt_f32_e64 s[0:1], |v28|, s35
	v_exp_f32_e32 v24, v24
	v_exp_f32_e32 v25, v25
	v_cndmask_b32_e64 v28, v28, v110, s[0:1]
	v_cndmask_b32_e32 v110, 0, v242, vcc
	v_sub_f32_e32 v28, v28, v110
	v_add_f32_e32 v28, v96, v28
	v_sub_f32_e32 v28, -0.5, v28
	v_mul_f32_e32 v28, 0x3fb8aa3b, v28
	v_exp_f32_e32 v28, v28
	v_pk_add_f32 v[24:25], v[24:25], 1.0 op_sel_hi:[1,0]
	v_lshlrev_b32_e32 v100, 16, v56
	v_and_b32_e32 v101, 0xffff0000, v56
	v_xor_b32_e32 v96, 0x80000000, v28
	v_add_f32_e32 v28, v29, v97
	v_max_f32_e64 v29, -v28, 0
	v_mul_f32_e64 v28, |v28|, s26
	v_exp_f32_e32 v28, v28
	v_add_f32_e32 v30, v30, v98
	v_add_f32_e32 v26, v26, v102
	v_add_f32_e32 v27, v27, v103
	v_add_f32_e32 v28, 1.0, v28
	v_cmp_gt_f32_e32 vcc, s6, v28
	v_mul_f32_e32 v26, 0xbfb8aa3b, v26
	v_mul_f32_e32 v27, 0xbfb8aa3b, v27
	v_cndmask_b32_e64 v97, 0, 32, vcc
	v_ldexp_f32 v28, v28, v97
	v_log_f32_e32 v28, v28
	v_exp_f32_e32 v26, v26
	v_exp_f32_e32 v27, v27
	v_add_f32_e32 v20, v20, v64
	v_mul_f32_e32 v97, 0x3f317217, v28
	v_fma_f32 v97, v28, s34, -v97
	v_fmac_f32_e32 v97, 0x3377d1cf, v28
	v_fmac_f32_e32 v97, 0x3f317217, v28
	v_cmp_lt_f32_e64 s[0:1], |v28|, s35
	v_pk_add_f32 v[26:27], v[26:27], 1.0 op_sel_hi:[1,0]
	v_add_f32_e32 v16, v16, v80
	v_cndmask_b32_e64 v28, v28, v97, s[0:1]
	v_cndmask_b32_e32 v97, 0, v242, vcc
	v_sub_f32_e32 v28, v28, v97
	v_add_f32_e32 v28, v29, v28
	v_sub_f32_e32 v28, -0.5, v28
	v_mul_f32_e32 v28, 0x3fb8aa3b, v28
	v_exp_f32_e32 v28, v28
	v_and_b32_e32 v29, 0xffff0000, v60
	v_xor_b32_e32 v97, 0x80000000, v28
	v_lshlrev_b32_e32 v28, 16, v60
	v_pk_fma_f32 v[100:101], v[178:179], v[100:101], v[28:29] op_sel_hi:[0,1,1] neg_lo:[0,0,1] neg_hi:[0,0,1]
	v_pk_fma_f32 v[28:29], v[84:85], v[100:101], v[28:29]
	v_add_f32_e32 v17, v17, v81
	v_rcp_f32_e32 v25, v25
	v_mul_f32_e32 v16, 0xbfb8aa3b, v16
	v_mul_f32_e32 v17, 0xbfb8aa3b, v17
	v_exp_f32_e32 v16, v16
	v_rcp_f32_e32 v24, v24
	v_max_f32_e64 v56, -v30, 0
	v_mul_f32_e64 v30, |v30|, s26
	v_exp_f32_e32 v30, v30
	v_pk_add_f32 v[84:85], v[24:25], -1.0 op_sel_hi:[1,0]
	v_exp_f32_e32 v17, v17
	v_pk_fma_f32 v[84:85], v[92:93], v[84:85], 1.0 op_sel_hi:[1,1,0]
	v_add_f32_e32 v30, 1.0, v30
	v_cmp_gt_f32_e32 vcc, s6, v30
	v_pk_mul_f32 v[84:85], v[28:29], v[84:85]
	v_pk_add_f32 v[16:17], v[16:17], 1.0 op_sel_hi:[1,0]
	v_cndmask_b32_e64 v60, 0, 32, vcc
	v_ldexp_f32 v30, v30, v60
	v_log_f32_e32 v30, v30
	v_pk_mul_f32 v[92:93], v[180:181], v[84:85]
	v_add_f32_e32 v22, v22, v66
	v_fmac_f32_e32 v159, v88, v92
	v_mul_f32_e32 v60, 0x3f317217, v30
	v_fma_f32 v60, v30, s34, -v60
	v_fmac_f32_e32 v60, 0x3377d1cf, v30
	v_fmac_f32_e32 v60, 0x3f317217, v30
	v_cmp_lt_f32_e64 s[0:1], |v30|, s35
	v_fmac_f32_e32 v159, v89, v93
	v_add_f32_e32 v18, v18, v82
	v_cndmask_b32_e64 v30, v30, v60, s[0:1]
	v_cndmask_b32_e32 v60, 0, v242, vcc
	v_sub_f32_e32 v30, v30, v60
	v_add_f32_e32 v30, v56, v30
	v_sub_f32_e32 v30, -0.5, v30
	v_mul_f32_e32 v30, 0x3fb8aa3b, v30
	v_exp_f32_e32 v30, v30
	v_add_f32_e32 v19, v19, v83
	v_mul_f32_e32 v18, 0xbfb8aa3b, v18
	v_mul_f32_e32 v19, 0xbfb8aa3b, v19
	v_xor_b32_e32 v88, 0x80000000, v30
	v_add_f32_e32 v30, v31, v99
	v_max_f32_e64 v31, -v30, 0
	v_mul_f32_e64 v30, |v30|, s26
	v_exp_f32_e32 v30, v30
	v_exp_f32_e32 v18, v18
	v_exp_f32_e32 v19, v19
	v_lshlrev_b32_e32 v66, 16, v36
	v_add_f32_e32 v30, 1.0, v30
	v_cmp_gt_f32_e32 vcc, s6, v30
	v_pk_add_f32 v[18:19], v[18:19], 1.0 op_sel_hi:[1,0]
	v_pk_mul_f32 v[28:29], v[28:29], v[48:49]
	v_cndmask_b32_e64 v56, 0, 32, vcc
	v_ldexp_f32 v30, v30, v56
	v_log_f32_e32 v30, v30
	s_nop 0
	v_mul_f32_e32 v56, 0x3f317217, v30
	v_fma_f32 v56, v30, s34, -v56
	v_fmac_f32_e32 v56, 0x3377d1cf, v30
	v_fmac_f32_e32 v56, 0x3f317217, v30
	v_cmp_lt_f32_e64 s[0:1], |v30|, s35
	s_nop 1
	v_cndmask_b32_e64 v30, v30, v56, s[0:1]
	v_cndmask_b32_e32 v56, 0, v242, vcc
	v_sub_f32_e32 v30, v30, v56
	v_add_f32_e32 v30, v31, v30
	v_sub_f32_e32 v30, -0.5, v30
	v_mul_f32_e32 v30, 0x3fb8aa3b, v30
	v_exp_f32_e32 v30, v30
	v_and_b32_e32 v31, 0xffff0000, v61
	v_lshlrev_b32_e32 v56, 16, v57
	v_and_b32_e32 v57, 0xffff0000, v57
	v_xor_b32_e32 v89, 0x80000000, v30
	v_lshlrev_b32_e32 v30, 16, v61
	v_pk_fma_f32 v[56:57], v[178:179], v[56:57], v[30:31] op_sel_hi:[0,1,1] neg_lo:[0,0,1] neg_hi:[0,0,1]
	v_pk_fma_f32 v[30:31], v[86:87], v[56:57], v[30:31]
	v_rcp_f32_e32 v27, v27
	v_rcp_f32_e32 v26, v26
	s_nop 0
	v_pk_add_f32 v[56:57], v[26:27], -1.0 op_sel_hi:[1,0]
	s_nop 0
	v_pk_fma_f32 v[56:57], v[94:95], v[56:57], 1.0 op_sel_hi:[1,1,0]
	s_nop 0
	v_pk_mul_f32 v[56:57], v[30:31], v[56:57]
	v_pk_mul_f32 v[30:31], v[30:31], v[50:51]
	v_pk_mul_f32 v[60:61], v[108:109], v[56:57]
	v_pk_mul_f32 v[50:51], v[30:31], v[30:31]
	v_fmac_f32_e32 v159, v90, v60
	v_max_f32_e64 v60, -v20, 0
	v_mul_f32_e64 v20, |v20|, s26
	v_exp_f32_e32 v20, v20
	v_fmac_f32_e32 v159, v91, v61
	v_add_f32_e32 v20, 1.0, v20
	v_cmp_gt_f32_e32 vcc, s6, v20
	s_nop 1
	v_cndmask_b32_e64 v61, 0, 32, vcc
	v_ldexp_f32 v20, v20, v61
	v_log_f32_e32 v20, v20
	s_nop 0
	v_mul_f32_e32 v61, 0x3f317217, v20
	v_fma_f32 v61, v20, s34, -v61
	v_fmac_f32_e32 v61, 0x3377d1cf, v20
	v_fmac_f32_e32 v61, 0x3f317217, v20
	v_cmp_lt_f32_e64 s[0:1], |v20|, s35
	s_nop 1
	v_cndmask_b32_e64 v20, v20, v61, s[0:1]
	v_cndmask_b32_e32 v61, 0, v242, vcc
	v_sub_f32_e32 v20, v20, v61
	v_add_f32_e32 v20, v60, v20
	v_sub_f32_e32 v20, -0.5, v20
	v_mul_f32_e32 v20, 0x3fb8aa3b, v20
	v_exp_f32_e32 v20, v20
	v_and_b32_e32 v61, 0xffff0000, v58
	v_xor_b32_e32 v64, 0x80000000, v20
	v_add_f32_e32 v20, v21, v65
	v_max_f32_e64 v21, -v20, 0
	v_mul_f32_e64 v20, |v20|, s26
	v_exp_f32_e32 v20, v20
	s_nop 0
	v_add_f32_e32 v20, 1.0, v20
	v_cmp_gt_f32_e32 vcc, s6, v20
	s_nop 1
	v_cndmask_b32_e64 v60, 0, 32, vcc
	v_ldexp_f32 v20, v20, v60
	v_log_f32_e32 v20, v20
	s_nop 0
	v_mul_f32_e32 v60, 0x3f317217, v20
	v_fma_f32 v60, v20, s34, -v60
	v_fmac_f32_e32 v60, 0x3377d1cf, v20
	v_fmac_f32_e32 v60, 0x3f317217, v20
	v_cmp_lt_f32_e64 s[0:1], |v20|, s35
	s_nop 1
	v_cndmask_b32_e64 v20, v20, v60, s[0:1]
	v_cndmask_b32_e32 v60, 0, v242, vcc
	v_sub_f32_e32 v20, v20, v60
	v_add_f32_e32 v20, v21, v20
	v_sub_f32_e32 v20, -0.5, v20
	v_mul_f32_e32 v20, 0x3fb8aa3b, v20
	v_exp_f32_e32 v20, v20
	v_and_b32_e32 v21, 0xffff0000, v62
	v_lshlrev_b32_e32 v60, 16, v58
	v_xor_b32_e32 v65, 0x80000000, v20
	v_lshlrev_b32_e32 v20, 16, v62
	v_pk_fma_f32 v[60:61], v[178:179], v[60:61], v[20:21] op_sel_hi:[0,1,1] neg_lo:[0,0,1] neg_hi:[0,0,1]
	v_pk_fma_f32 v[20:21], v[52:53], v[60:61], v[20:21]
	v_rcp_f32_e32 v17, v17
	v_max_f32_e64 v58, -v22, 0
	v_mul_f32_e64 v22, |v22|, s26
	v_exp_f32_e32 v22, v22
	v_rcp_f32_e32 v16, v16
	s_nop 0
	v_pk_add_f32 v[52:53], v[16:17], -1.0 op_sel_hi:[1,0]
	v_add_f32_e32 v22, 1.0, v22
	v_cmp_gt_f32_e32 vcc, s6, v22
	v_pk_fma_f32 v[52:53], v[76:77], v[52:53], 1.0 op_sel_hi:[1,1,0]
	s_nop 0
	v_cndmask_b32_e64 v62, 0, 32, vcc
	v_ldexp_f32 v22, v22, v62
	v_log_f32_e32 v22, v22
	v_pk_mul_f32 v[60:61], v[20:21], v[52:53]
	v_pk_mul_f32 v[20:21], v[20:21], v[68:69]
	v_pk_mul_f32 v[76:77], v[104:105], v[60:61]
	v_mul_f32_e32 v62, 0x3f317217, v22
	v_fma_f32 v62, v22, s34, -v62
	v_fmac_f32_e32 v62, 0x3377d1cf, v22
	v_fmac_f32_e32 v62, 0x3f317217, v22
	v_cmp_lt_f32_e64 s[0:1], |v22|, s35
	v_fmac_f32_e32 v159, v72, v76
	v_fmac_f32_e32 v159, v73, v77
	v_cndmask_b32_e64 v22, v22, v62, s[0:1]
	v_cndmask_b32_e32 v62, 0, v242, vcc
	v_sub_f32_e32 v22, v22, v62
	v_add_f32_e32 v22, v58, v22
	v_sub_f32_e32 v22, -0.5, v22
	v_mul_f32_e32 v22, 0x3fb8aa3b, v22
	v_exp_f32_e32 v22, v22
	v_pk_mul_f32 v[52:53], v[20:21], v[20:21]
	v_xor_b32_e32 v68, 0x80000000, v22
	v_add_f32_e32 v22, v23, v67
	v_max_f32_e64 v23, -v22, 0
	v_mul_f32_e64 v22, |v22|, s26
	v_exp_f32_e32 v22, v22
	v_and_b32_e32 v67, 0xffff0000, v36
	v_lshlrev_b32_e32 v36, 16, v37
	v_and_b32_e32 v37, 0xffff0000, v37
	v_add_f32_e32 v22, 1.0, v22
	v_cmp_gt_f32_e32 vcc, s6, v22
	s_nop 1
	v_cndmask_b32_e64 v58, 0, 32, vcc
	v_ldexp_f32 v22, v22, v58
	v_log_f32_e32 v22, v22
	s_nop 0
	v_mul_f32_e32 v58, 0x3f317217, v22
	v_fma_f32 v58, v22, s34, -v58
	v_fmac_f32_e32 v58, 0x3377d1cf, v22
	v_fmac_f32_e32 v58, 0x3f317217, v22
	v_cmp_lt_f32_e64 s[0:1], |v22|, s35
	s_nop 1
	v_cndmask_b32_e64 v22, v22, v58, s[0:1]
	v_cndmask_b32_e32 v58, 0, v242, vcc
	v_sub_f32_e32 v22, v22, v58
	v_add_f32_e32 v22, v23, v22
	v_sub_f32_e32 v22, -0.5, v22
	v_mul_f32_e32 v22, 0x3fb8aa3b, v22
	v_exp_f32_e32 v22, v22
	v_and_b32_e32 v23, 0xffff0000, v63
	v_lshlrev_b32_e32 v58, 16, v59
	v_and_b32_e32 v59, 0xffff0000, v59
	v_xor_b32_e32 v69, 0x80000000, v22
	v_lshlrev_b32_e32 v22, 16, v63
	v_pk_fma_f32 v[58:59], v[178:179], v[58:59], v[22:23] op_sel_hi:[0,1,1] neg_lo:[0,0,1] neg_hi:[0,0,1]
	v_pk_fma_f32 v[22:23], v[54:55], v[58:59], v[22:23]
	v_rcp_f32_e32 v19, v19
	v_rcp_f32_e32 v18, v18
	s_nop 0
	v_pk_add_f32 v[54:55], v[18:19], -1.0 op_sel_hi:[1,0]
	s_nop 0
	v_pk_fma_f32 v[54:55], v[78:79], v[54:55], 1.0 op_sel_hi:[1,1,0]
	s_nop 0
	v_pk_mul_f32 v[54:55], v[22:23], v[54:55]
	v_pk_mul_f32 v[22:23], v[22:23], v[70:71]
	v_pk_mul_f32 v[58:59], v[106:107], v[54:55]
	v_pk_mul_f32 v[62:63], v[22:23], v[22:23]
	v_fmac_f32_e32 v159, v74, v58
	v_fmac_f32_e32 v159, v75, v59
	v_lshlrev_b32_e32 v58, 16, v40
	v_and_b32_e32 v59, 0xffff0000, v40
	v_lshlrev_b32_e32 v40, 16, v41
	v_and_b32_e32 v41, 0xffff0000, v41
	v_pk_fma_f32 v[36:37], v[178:179], v[36:37], v[40:41] op_sel_hi:[0,1,1] neg_lo:[0,0,1] neg_hi:[0,0,1]
	v_pk_fma_f32 v[36:37], v[46:47], v[36:37], v[40:41]
	v_lshlrev_b32_e32 v40, 16, v42
	v_and_b32_e32 v41, 0xffff0000, v42
	v_lshlrev_b32_e32 v46, 16, v38
	v_and_b32_e32 v47, 0xffff0000, v38
	v_pk_fma_f32 v[46:47], v[178:179], v[46:47], v[40:41] op_sel_hi:[0,1,1] neg_lo:[0,0,1] neg_hi:[0,0,1]
	v_pk_fma_f32 v[40:41], v[32:33], v[46:47], v[40:41]
	v_lshlrev_b32_e32 v32, 16, v43
	v_and_b32_e32 v33, 0xffff0000, v43
	v_lshlrev_b32_e32 v38, 16, v39
	v_and_b32_e32 v39, 0xffff0000, v39
	v_pk_fma_f32 v[38:39], v[178:179], v[38:39], v[32:33] op_sel_hi:[0,1,1] neg_lo:[0,0,1] neg_hi:[0,0,1]
	v_pk_fma_f32 v[66:67], v[178:179], v[66:67], v[58:59] op_sel_hi:[0,1,1] neg_lo:[0,0,1] neg_hi:[0,0,1]
	v_pk_fma_f32 v[38:39], v[34:35], v[38:39], v[32:33]
	v_cvt_pk_bf16_f32 v32, v180, v181
	v_cvt_pk_bf16_f32 v33, v108, v109
	v_cvt_pk_bf16_f32 v34, v104, v105
	v_cvt_pk_bf16_f32 v35, v106, v107
	v_pk_fma_f32 v[44:45], v[44:45], v[66:67], v[58:59]
	ds_write_b128 v198, v[32:35] offset:1024
	ds_read_b128 v[246:249], v199 offset:1024
	v_lshl_add_u64 v[250:251], v[208:209], 0, v[202:203]
	s_waitcnt lgkmcnt(2)
	global_store_dwordx4 v[230:231], v[232:235], off
	s_nop 1
	v_cvt_pk_bf16_f32 v32, v84, v85
	v_cvt_pk_bf16_f32 v33, v56, v57
	v_cvt_pk_bf16_f32 v34, v60, v61
	v_cvt_pk_bf16_f32 v35, v54, v55
	ds_write_b128 v198, v[32:35]
	ds_read_b128 v[232:235], v199
	v_lshl_add_u64 v[230:231], v[208:209], 0, v[202:203]
	s_waitcnt lgkmcnt(2)
	global_store_dwordx4 v[250:251], v[246:249], off offset:64
	s_nop 1
	v_cvt_pk_bf16_f32 v32, v44, v45
	v_cvt_pk_bf16_f32 v33, v36, v37
	v_cvt_pk_bf16_f32 v34, v40, v41
	v_cvt_pk_bf16_f32 v35, v38, v39
	ds_write_b128 v198, v[32:35] offset:1024
	ds_read_b128 v[246:249], v199 offset:1024
	v_lshl_add_u64 v[250:251], v[208:209], 0, v[202:203]
	s_waitcnt lgkmcnt(2)
	global_store_dwordx4 v[230:231], v[232:235], off offset:576
	s_nop 1
	v_cvt_pk_bf16_f32 v32, v96, v97
	v_cvt_pk_bf16_f32 v33, v88, v89
	v_cvt_pk_bf16_f32 v34, v64, v65
	v_cvt_pk_bf16_f32 v35, v68, v69
	ds_write_b128 v198, v[32:35]
	ds_read_b128 v[232:235], v199
	v_lshl_add_u64 v[230:231], v[208:209], 0, v[202:203]
	s_waitcnt lgkmcnt(2)
	global_store_dwordx4 v[250:251], v[246:249], off offset:1088
	ds_write_b128 v198, v[0:3] offset:1024
	ds_read_b128 v[246:249], v199 offset:1024
	v_lshl_add_u64 v[250:251], v[212:213], 0, v[204:205]
	s_waitcnt lgkmcnt(2)
	global_store_dwordx4 v[230:231], v[232:235], off offset:2624
	s_nop 0
	v_pk_mul_f32 v[32:33], v[8:9], v[8:9]
	v_pk_mul_f32 v[2:3], v[210:211], v[14:15]
	v_pk_mul_f32 v[14:15], v[10:11], v[10:11]
	v_add_f32_e32 v32, v32, v33
	v_add_f32_e32 v14, v14, v32
	v_add_f32_e32 v14, v15, v14
	v_add_f32_e32 v12, v14, v12
	v_pk_mul_f32 v[4:5], v[2:3], v[2:3]
	v_add_f32_e32 v12, v13, v12
	v_add_f32_e32 v4, v4, v12
	v_pk_mul_f32 v[34:35], v[28:29], v[28:29]
	v_add_f32_e32 v4, v5, v4
	v_add_f32_e32 v4, v4, v34
	v_add_f32_e32 v4, v35, v4
	v_add_f32_e32 v4, v50, v4
	v_and_b32_e32 v1, 64, v243
	v_add_f32_e32 v4, v51, v4
	v_xor_b32_e32 v0, 16, v243
	v_add_u32_e32 v1, 64, v1
	v_add_f32_e32 v4, v4, v52
	v_cmp_lt_i32_e32 vcc, v0, v1
	v_add_f32_e32 v4, v53, v4
	v_add_f32_e32 v4, v62, v4
	v_cndmask_b32_e32 v0, v243, v0, vcc
	v_lshlrev_b32_e32 v36, 2, v0
	v_add_f32_e32 v4, v63, v4
	ds_bpermute_b32 v5, v36, v4
	v_xor_b32_e32 v0, 32, v243
	v_cmp_lt_i32_e32 vcc, v0, v1
	s_waitcnt lgkmcnt(0)
	v_add_f32_e32 v4, v4, v5
	v_cndmask_b32_e32 v0, v243, v0, vcc
	v_lshlrev_b32_e32 v37, 2, v0
	ds_bpermute_b32 v5, v37, v4
	ds_bpermute_b32 v0, v36, v159
	s_waitcnt lgkmcnt(0)
	v_add_f32_e32 v4, v4, v5
	v_cmp_gt_f32_e32 vcc, s36, v4
	v_mul_f32_e32 v5, 0x4f800000, v4
	v_add_f32_e32 v0, v159, v0
	v_cndmask_b32_e32 v4, v4, v5, vcc
	v_sqrt_f32_e32 v5, v4
	ds_bpermute_b32 v1, v37, v0
	v_add_u32_e32 v12, -1, v5
	v_fma_f32 v13, -v12, v5, v4
	v_cmp_ge_f32_e64 s[0:1], 0, v13
	v_add_u32_e32 v13, 1, v5
	s_nop 0
	v_cndmask_b32_e64 v12, v5, v12, s[0:1]
	v_fma_f32 v5, -v13, v5, v4
	v_cmp_lt_f32_e64 s[0:1], 0, v5
	s_nop 1
	v_cndmask_b32_e64 v5, v12, v13, s[0:1]
	v_mul_f32_e32 v12, 0x37800000, v5
	v_cndmask_b32_e32 v5, v5, v12, vcc
	v_cmp_class_f32_e32 vcc, v4, v237
	s_nop 1
	v_cndmask_b32_e32 v4, v5, v4, vcc
	v_max_f32_e32 v4, 0x2b8cbccc, v4
	v_rcp_f32_e32 v12, v4
	s_nop 0
	v_pk_mul_f32 v[4:5], v[8:9], v[12:13] op_sel_hi:[1,0]
	v_pk_mul_f32 v[10:11], v[10:11], v[12:13] op_sel_hi:[1,0]
	v_pk_mul_f32 v[6:7], v[6:7], v[12:13] op_sel_hi:[1,0]
	v_pk_mul_f32 v[34:35], v[2:3], v[12:13] op_sel_hi:[1,0]
	v_pk_mul_f32 v[8:9], v[116:117], v[4:5]
	v_pk_mul_f32 v[14:15], v[118:119], v[10:11]
	v_pk_mul_f32 v[32:33], v[188:189], v[6:7]
	v_pk_mul_f32 v[36:37], v[206:207], v[34:35]
	v_cvt_pk_bf16_f32 v2, v4, v5
	v_cvt_pk_bf16_f32 v3, v10, v11
	v_cvt_pk_bf16_f32 v4, v6, v7
	v_cvt_pk_bf16_f32 v5, v34, v35
	ds_write_b128 v198, v[2:5]
	ds_read_b128 v[232:235], v199
	v_lshl_add_u64 v[230:231], v[208:209], 0, v[202:203]
	s_waitcnt lgkmcnt(2)
	global_store_dwordx4 v[250:251], v[246:249], off offset:64
	v_pk_mul_f32 v[10:11], v[20:21], v[12:13] op_sel_hi:[1,0]
	s_nop 0
	v_cvt_pk_bf16_f32 v2, v8, v9
	v_cvt_pk_bf16_f32 v3, v14, v15
	v_cvt_pk_bf16_f32 v4, v32, v33
	v_cvt_pk_bf16_f32 v5, v36, v37
	ds_write_b128 v198, v[2:5] offset:1024
	ds_read_b128 v[246:249], v199 offset:1024
	v_lshl_add_u64 v[250:251], v[208:209], 0, v[202:203]
	s_waitcnt lgkmcnt(2)
	global_store_dwordx4 v[230:231], v[232:235], off offset:1536
	v_pk_mul_f32 v[14:15], v[16:17], v[10:11]
	s_nop 0
	v_pk_mul_f32 v[2:3], v[28:29], v[12:13] op_sel_hi:[1,0]
	v_pk_mul_f32 v[4:5], v[30:31], v[12:13] op_sel_hi:[1,0]
	v_pk_mul_f32 v[12:13], v[22:23], v[12:13] op_sel_hi:[1,0]
	v_pk_mul_f32 v[6:7], v[24:25], v[2:3]
	v_pk_mul_f32 v[8:9], v[26:27], v[4:5]
	v_pk_mul_f32 v[16:17], v[18:19], v[12:13]
	v_cvt_pk_bf16_f32 v2, v2, v3
	v_cvt_pk_bf16_f32 v3, v4, v5
	v_cvt_pk_bf16_f32 v4, v10, v11
	v_cvt_pk_bf16_f32 v5, v12, v13
	ds_write_b128 v198, v[2:5]
	ds_read_b128 v[232:235], v199
	v_lshl_add_u64 v[230:231], v[208:209], 0, v[202:203]
	s_waitcnt lgkmcnt(2)
	global_store_dwordx4 v[250:251], v[246:249], off offset:2048
	s_nop 1
	v_cvt_pk_bf16_f32 v2, v6, v7
	v_cvt_pk_bf16_f32 v3, v8, v9
	v_cvt_pk_bf16_f32 v4, v14, v15
	v_cvt_pk_bf16_f32 v5, v16, v17
	ds_write_b128 v198, v[2:5] offset:1024
	ds_read_b128 v[246:249], v199 offset:1024
	v_lshl_add_u64 v[250:251], v[208:209], 0, v[202:203]
	s_waitcnt lgkmcnt(2)
	global_store_dwordx4 v[230:231], v[232:235], off offset:1600
	s_waitcnt lgkmcnt(0)
	global_store_dwordx4 v[250:251], v[246:249], off offset:2112
	s_and_saveexec_b64 s[0:1], s[8:9]
	s_cbranch_execz .LBB0_341
	v_lshl_add_u64 v[2:3], v[176:177], 4, s[16:17]
	s_waitcnt lgkmcnt(0)
	v_add_f32_e32 v0, v0, v1
	global_store_dword v[2:3], v0, off
	s_branch .LBB0_341
